# prologue: half of the workgroups (bx bit 3) run the SSM chunk-matrix block before the weight streaming, the other half after, so memory-bound and compute-bound prologue work overlap
# speedup vs baseline: 1.0168x; 1.0003x over previous
.LBB0_3:
	s_or_b64 exec, exec, s[2:3]
	s_mov_b64 s[2:3], s[0:1]
	s_waitcnt lgkmcnt(0)
	s_mov_b32 s4, s13
	s_mov_b32 s5, s12
	s_barrier
	s_load_dwordx4 s[4:7], s[2:3], 0xe8
	s_mov_b32 s33, 0
	s_waitcnt lgkmcnt(0)
	s_add_u32 s20, s4, 0x4000
	s_addc_u32 s21, s5, 0
	s_getreg_b32 s32, hwreg(HW_REG_XCC_ID, 0, 4)
	s_add_i32 s32, s32, 1
	s_add_u32 s8, s4, 0x20000
	s_addc_u32 s9, s5, 0
	v_mov_b32_e32 v0, s32
	s_lshl_b32 s32, s12, 2
	v_mov_b32_e32 v1, s32
	s_nop 0
	global_store_dword v1, v0, s[8:9]
	s_mov_b32 s32, 0
	v_writelane_b32 v255, s4, 2
	s_sub_i32 s2, s7, s6
	s_cmp_gt_i32 s2, 1
	v_writelane_b32 v255, s5, 3
	v_writelane_b32 v255, s6, 4
	v_writelane_b32 v255, s7, 5
	s_mov_b32 s2, 0
	v_writelane_b32 v255, s2, 6
	s_cbranch_scc0 .LBB0_8
	v_mov_b32_e32 v0, v220
	s_getreg_b32 s2, hwreg(HW_REG_XCC_ID, 0, 4)
	s_and_b32 s33, s2, 15
	v_cmp_eq_u32_e32 vcc, 0, v0
	s_and_saveexec_b64 s[2:3], vcc
	s_cbranch_execz .LBB0_7
	s_mov_b64 s[4:5], exec
	v_mbcnt_lo_u32_b32 v0, s4, 0
	v_mbcnt_hi_u32_b32 v0, s5, v0
	v_cmp_eq_u32_e32 vcc, 0, v0
	s_and_b64 s[6:7], exec, vcc
	s_mov_b64 exec, s[6:7]
	s_cbranch_execz .LBB0_7
	s_lshl_b32 s6, s33, 8
	s_bcnt1_i32_b64 s4, s[4:5]
	v_mov_b32_e32 v0, s6
	v_mov_b32_e32 v1, s4
	global_atomic_add v0, v1, s[20:21] offset:1024

.Lp0_again:
	s_mov_b64 s[24:25], s[0:1]
	s_mov_b32 s26, s12
	s_mov_b32 s28, s13
	v_mov_b32_e32 v44, v220
	s_nop 0
	v_readfirstlane_b32 s2, v44
	s_ashr_i32 s27, s2, 6
	s_lshl_b32 s2, s26, 3
	v_and_b32_e32 v46, 63, v44
	s_add_i32 s29, s27, s2
	s_cmp_lg_u32 s32, 0
	s_cbranch_scc1 .Lp0_tr_go
	s_bitcmp1_b32 s12, 3
	s_cbranch_scc0 .Lp0_tr_go
	s_mov_b32 s32, 1
	v_lshlrev_b32_e32 v13, 3, v46
	v_lshlrev_b32_e32 v47, 3, v44
	s_load_dwordx2 s[8:9], s[24:25], 0xe8
	s_waitcnt lgkmcnt(0)
	s_branch .Lp0_ssm_entry
.Lp0_tr_go:
	s_cmp_gt_i32 s29, 0xd7ff
	v_lshlrev_b32_e32 v13, 3, v46
	s_cbranch_scc1 .LBB0_58
	s_lshl_b32 s30, s28, 3
	s_load_dwordx2 s[2:3], s[24:25], 0x68
	s_load_dwordx2 s[4:5], s[24:25], 0xd0
	s_load_dwordx2 s[6:7], s[24:25], 0xc0
	s_load_dwordx2 s[8:9], s[24:25], 0xe8
	v_lshrrev_b32_e32 v0, 3, v46
	v_and_b32_e32 v1, 7, v46
	v_lshlrev_b32_e32 v2, 4, v1
	v_lshlrev_b32_e32 v3, 3, v0
	v_lshlrev_b32_e32 v4, 2, v1
	v_lshlrev_b32_e32 v5, 4, v0
	s_waitcnt lgkmcnt(0)
	s_mov_b32 s11, s29
	s_cmp_ge_u32 s11, 0x6c00
	s_cselect_b32 s16, 0x6c00, 0
	s_cselect_b32 s10, 2, 0
	s_sub_u32 s11, s11, s16
	s_cmp_ge_u32 s11, 0x3600
	s_cselect_b32 s16, 0x3600, 0
	s_cselect_b32 s17, 1, 0
	s_sub_u32 s11, s11, s16
	s_add_u32 s10, s10, s17
	s_cmp_lt_u32 s11, 0x2400
	s_cbranch_scc1 .Ltr_in1
	s_cmp_lt_u32 s11, 0x3400
	s_cbranch_scc1 .Ltr_out1
	s_sub_u32 s11, s11, 0x3400
	s_and_b32 s16, s11, 15
	s_lshr_b32 s17, s11, 4
	s_movk_i32 s14, 0x2000
	s_movk_i32 s15, 0x800
	s_mov_b32 s34, 0x10000
	s_lshl_b32 s31, s10, 23
	s_lshl_b32 s11, s16, 19
	s_add_u32 s31, s31, s11
	s_lshl_b32 s11, s17, 8
	s_add_u32 s31, s31, s11
	s_add_u32 s31, s6, s31
	s_addc_u32 s11, s7, 0
	s_bfe_u32 s14, s17, 0x30001
	s_lshl_b32 s14, s14, 8
	s_lshr_b32 s15, s17, 4
	s_lshl_b32 s15, s15, 7
	s_add_u32 s14, s14, s15
	s_and_b32 s15, s17, 1
	s_lshl_b32 s15, s15, 6
	s_add_u32 s14, s14, s15
	s_lshl_b32 s14, s14, 11
	s_lshl_b32 s15, s16, 7
	s_add_u32 s14, s14, s15
	s_lshl_b32 s15, s10, 22
	s_add_u32 s14, s14, s15
	s_add_u32 s17, s14, 0xae00000
	s_mov_b32 s16, s31
	s_mov_b32 s31, s17
	s_mov_b32 s17, s11
	s_movk_i32 s14, 0x2000
	s_movk_i32 s15, 0x800
	s_branch .Ltr_dec1

.LBB0_115:
	s_or_b64 exec, exec, s[2:3]
	s_andn2_b64 vcc, exec, s[14:15]
	s_barrier
	s_cbranch_vccnz .LBB0_219
	s_cmp_eq_u32 s32, 2
	s_cbranch_scc1 .LBB0_219
.Lp0_ssm_entry:
	v_lshrrev_b32_e32 v0, 6, v44
	s_movk_i32 s4, 0x2200
	s_add_u32 s30, s8, 0x300000
	v_bfe_u32 v2, v44, 4, 4
	v_ashrrev_i32_e32 v3, 8, v44
	v_mul_lo_u32 v0, v0, s4
	s_addc_u32 s31, s9, 0
	v_mad_i32_i24 v6, v3, 17, v2
	v_add3_u32 v50, 0, v0, v13
	v_and_b32_e32 v4, 15, v44
	v_lshl_add_u32 v51, v6, 9, 0
	v_and_b32_e32 v6, 0x3ffff00, v44
	v_lshlrev_b32_e32 v2, 4, v2
	s_add_u32 s50, s8, 0xe00000
	v_or_b32_e32 v0, v0, v13
	v_or3_b32 v2, v2, v6, v4
	s_addc_u32 s51, s9, 0
	v_add_u32_e32 v52, 0, v0
	v_add_u32_e32 v0, 0, v47
	s_movk_i32 s29, 0x80
	v_lshlrev_b32_e32 v1, 7, v44
	s_movk_i32 s4, 0x800
	v_lshlrev_b32_e32 v5, 9, v4
	v_lshlrev_b32_e32 v2, 6, v2
	s_movk_i32 s6, 0x2000
	s_add_u32 s52, s8, 0x2e00000
	s_movk_i32 s8, 0x4000
	s_mov_b32 s10, 0x8400
	v_add_u32_e32 v53, 0x8400, v0
	v_lshl_add_u32 v0, v3, 13, 0
	s_mov_b32 s34, 0x6dc9c883
	v_cmp_gt_i32_e64 s[2:3], s29, v44
	v_and_b32_e32 v45, 0xffffffc0, v44
	v_mov_b32_e32 v49, 0
	v_cmp_gt_i32_e64 s[4:5], s4, v44
	v_cmp_gt_i32_e64 s[6:7], s6, v44
	s_addc_u32 s53, s9, 0
	v_cmp_gt_i32_e64 s[8:9], s8, v44
	v_add3_u32 v54, v0, v5, s10
	v_add_u32_e32 v55, 0x4400, v0
	s_mov_b32 s54, 0x3fb8aa3b
	s_mov_b32 s55, 0xc2ce8ed0
	s_mov_b32 s56, 0x42b17218
	s_mov_b32 s57, 0x7f800000
	s_mov_b32 s35, 0x3fc45f30
	v_mov_b32_e32 v56, 0xbf1f24be
	v_mov_b32_e32 v57, 0x3e642e9d
	s_movk_i32 s58, 0x1f8
	v_add_u32_e32 v58, 0, v1
	s_movk_i32 s59, 0x1000
	s_movk_i32 s60, 0x5ff
	v_add_u32_e32 v59, 0, v2
	s_movk_i32 s61, 0x1dff
	s_movk_i32 s62, 0xff
	s_mov_b32 s63, 0xc400
	s_movk_i32 s64, 0x3dff
	v_mov_b32_e32 v60, 0x7f800000
	v_mov_b32_e32 v61, 0x7fc00000
	s_branch .LBB0_118

.LBB0_219:
	s_cmp_eq_u32 s32, 1
	s_cbranch_scc0 .Lp0_done
	s_mov_b32 s32, 2
	s_branch .Lp0_again
